# v23 plus hot spilled wave masks kept in s98-s101 (12 v_readlane per unit -> s_mov_b64) and pass A S1 accumulator zero-inits moved onto the tile-skip paths only
# baseline (speedup 1.0000x reference)
.LBB0_661:
	v_writelane_b32 v233, s72, 28
	s_add_u32 s10, s86, 0x16b00000
	s_addc_u32 s11, s87, 0
	v_writelane_b32 v233, s73, 29
	v_writelane_b32 v233, s57, 30
	v_writelane_b32 v233, s71, 31
	s_add_u32 s0, s86, 0x1cd00000
	v_writelane_b32 v233, s0, 32
	s_addc_u32 s0, s87, 0
	v_writelane_b32 v233, s0, 33
	s_add_u32 s0, s84, 0x2000000
	s_addc_u32 s1, s85, 0
	s_add_u32 s50, s86, 0x1f700000
	v_writelane_b32 v233, s0, 34
	s_addc_u32 s51, s87, 0
	s_mov_b32 s73, 0x5040100
	v_writelane_b32 v233, s1, 35
	s_add_u32 s0, s86, 0x1f800000
	s_addc_u32 s1, s87, 0
	v_writelane_b32 v233, s0, 36
	s_ashr_i32 s71, s70, 31
	s_mov_b64 s[42:43], s[70:71]
	v_writelane_b32 v233, s1, 37
	s_ashr_i32 s0, s41, 31
	v_writelane_b32 v233, s0, 38
	s_lshl_b32 s0, s42, 5
	v_readlane_b32 s13, v233, 5
	s_and_b32 s15, s0, 0x60
	s_lshl_b32 s0, s13, 8
	s_add_i32 s48, 0, 0x12000
	s_ashr_i32 s14, s70, 3
	s_add_i32 s49, s48, s0
	s_cmp_lt_u32 s74, 64
	s_cselect_b64 s[24:25], -1, 0
	s_cmp_gt_u32 s74, 63
	s_cselect_b64 s[26:27], -1, 0
	s_cmpk_gt_u32 s74, 0x7f
	s_cselect_b64 s[0:1], -1, 0
	v_writelane_b32 v233, s0, 39
	s_cmpk_gt_u32 s74, 0xbf
	s_mul_i32 s4, s13, 0x480
	v_writelane_b32 v233, s1, 40
	s_cselect_b64 s[0:1], -1, 0
	v_writelane_b32 v233, s0, 41
	s_cmpk_gt_u32 s74, 0xff
	v_mov_b32_e32 v3, 0
	v_writelane_b32 v233, s1, 42
	s_cselect_b64 s[0:1], -1, 0
	v_writelane_b32 v233, s0, 43
	s_cmpk_gt_u32 s74, 0x13f
	s_waitcnt vmcnt(0)
	v_perm_b32 v88, v47, v0, s73
	v_writelane_b32 v233, s1, 44
	s_cselect_b64 s[0:1], -1, 0
	v_writelane_b32 v233, s0, 45
	s_cmpk_gt_u32 s74, 0x17f
	v_mov_b32_e32 v77, 0x260
	v_writelane_b32 v233, s1, 46
	s_cselect_b64 s[0:1], -1, 0
	v_writelane_b32 v233, s0, 47
	s_cmpk_gt_u32 s74, 0x1bf
	s_movk_i32 s76, 0x90
	v_writelane_b32 v233, s1, 48
	s_cselect_b64 s[0:1], -1, 0
	v_writelane_b32 v233, s0, 49
	s_cmpk_gt_u32 s74, 0x1ff
	v_mov_b64_e32 v[20:21], 0x1000
	v_writelane_b32 v233, s1, 50
	s_cselect_b64 s[0:1], -1, 0
	s_lshl_b32 s88, s13, 4
	v_writelane_b32 v233, s0, 51
	s_add_i32 s53, s88, 0
	s_lshr_b32 s5, s74, 7
	s_bfe_u32 s6, s74, 0x10006
	v_writelane_b32 v233, s1, 52
	s_cmpk_lt_u32 s74, 0x100
	s_mov_b32 s1, 0x9000
	s_cselect_b32 s0, 0, 0x2400
	s_cselect_b32 s7, s1, 0x1ce00
	s_movk_i32 s1, 0x4800
	s_cselect_b32 s8, s1, 0x6c00
	s_add_i32 s54, s0, 0
	s_bitcmp0_b32 s74, 7
	s_cselect_b32 s0, s1, 0x6c00
	s_add_i32 s55, s0, 0
	s_lshl_b32 s9, s6, 1
	s_cmpk_lt_u32 s74, 0x80
	s_cselect_b64 s[28:29], -1, 0
	s_cmp_eq_u32 s5, 2
	s_mov_b32 s0, 0x17200
	s_cselect_b32 s12, s0, 0x19600
	s_cmp_eq_u32 s5, 1
	s_cselect_b64 s[20:21], -1, 0
	s_and_b64 s[0:1], s[20:21], exec
	s_cselect_b32 s0, 0x14e00, s12
	s_add_i32 s56, s0, 0
	s_lshl_b32 s57, s6, 5
	s_lshl_b32 s58, s6, 6
	s_and_b32 s0, 64, s74
	s_cmp_eq_u32 s6, 0
	s_cselect_b64 s[30:31], -1, 0
	s_cmp_lg_u32 s0, 0
	s_cselect_b64 s[34:35], -1, 0
	s_or_b32 s62, s9, 1
	s_lshl_b32 s60, s62, 4
	s_lshl_b32 s61, s62, 5
	s_cmp_lg_u32 s13, 1
	s_mul_i32 s0, s13, 0x300
	s_cselect_b64 s[36:37], -1, 0
	s_add_i32 s64, s0, 0
	s_sub_i32 s63, s88, 64
	s_add_i32 s64, s64, 0x1ba00
	s_lshl_b32 s65, s13, 5
	s_cmpk_lt_u32 s74, 0xc0
	v_writelane_b32 v233, s74, 53
	s_cselect_b64 s[38:39], -1, 0
	s_add_i32 s0, s88, 16
	v_writelane_b32 v233, s0, 54
	s_lshl_b32 s0, s6, 3
	s_add_i32 s71, s0, 0
	s_lshl_b32 s0, s42, 9
	s_and_b32 s0, s0, 0x800
	v_writelane_b32 v233, s14, 56
	s_add_i32 s0, s14, s0
	v_writelane_b32 v233, s15, 57
	s_add_i32 s75, s0, s15
	s_load_dwordx2 s[40:41], s[82:83], 0x58
	s_load_dwordx4 s[12:15], s[82:83], 0x88
	s_lshl_b32 s69, s63, 1
	s_add_i32 s70, s69, 0
	s_lshl_b32 s1, s5, 6
	v_cndmask_b32_e64 v69, 0, 1, s[20:21]
	s_mul_i32 s59, s6, 0xa00
	s_mulk_i32 s62, 0x500
	s_add_i32 s66, s7, 0
	s_add_i32 s67, s8, 0
	s_and_b32 s68, s88, 48
	s_add_i32 s70, s70, 0x1ce00
	s_add_i32 s71, s71, s1
	s_add_i32 s72, s48, s65
	s_add_i32 s74, s4, 0
	s_add_i32 s77, 0, 0xfc00
	v_mov_b32_e32 v78, 0xf800000
	v_mov_b32_e32 v79, 0x4f800000
	v_mov_b32_e32 v124, v3
	v_mov_b32_e32 v125, v3
	v_mov_b32_e32 v80, 0x1e800
	v_mov_b32_e32 v81, 0x14400
	v_mov_b32_e32 v82, 0x900
	v_mov_b32_e32 v83, 0x1200
	v_mov_b32_e32 v87, 0x1b00
	s_mov_b32 s78, 0
	v_writelane_b32 v233, s42, 58
	s_mov_b32 s16, 0
	s_nop 0
	v_writelane_b32 v233, s43, 59
	v_mov_b32_e32 v213, v23
	v_ashrrev_i32_e32 v214, 3, v213
	v_add_u32_e32 v215, s33, v214
	v_mul_lo_u32 v216, v215, s76
	v_lshlrev_b32_e32 v217, 4, v213
	v_and_b32_e32 v218, 0x70, v217
	v_add3_u32 v130, 0, v216, v218
	v_and_b32_e32 v219, 0xffffff0, v213
	v_mul_lo_u32 v220, v219, s76
	v_lshlrev_b32_e32 v221, 1, v213
	v_add3_u32 v131, 0, v220, v221
	v_mov_b32_e32 v213, v23
	v_and_b32_e32 v214, 15, v213
	v_or_b32_e32 v215, s63, v214
	v_mul_lo_u32 v216, v215, s76
	v_and_b32_e32 v217, -16, v213
	v_add3_u32 v132, 0, v216, v217
	s_add_i32 s90, 0, 0x14e00
	v_ashrrev_i32_e32 v218, 3, v213
	v_add_u32_e32 v219, s33, v218
	v_mul_lo_u32 v220, v219, s76
	v_lshlrev_b32_e32 v221, 4, v213
	v_and_b32_e32 v222, 0x70, v221
	v_add3_u32 v133, s90, v220, v222
	s_add_i32 s91, 0, 0x14e00
	v_mov_b32_e32 v213, v23
	v_and_b32_e32 v214, 15, v213
	v_mul_u32_u24_e32 v215, 0x90, v214
	v_and_b32_e32 v216, -16, v213
	v_add3_u32 v134, s91, v215, v216
	s_add_i32 s92, 0, 0x1ba00
	v_ashrrev_i32_e32 v217, 4, v213
	s_movk_i32 s93, 0x300
	v_mul_lo_u32 v218, v217, s93
	v_mul_u32_u24_e32 v219, 48, v214
	v_add3_u32 v135, s92, v218, v219
	s_add_i32 s94, 0, 0x1ce00
	v_ashrrev_i32_e32 v220, 3, v213
	v_add_u32_e32 v221, s33, v220
	v_mul_lo_u32 v222, v221, s76
	v_lshlrev_b32_e32 v223, 4, v213
	v_and_b32_e32 v224, 0x70, v223
	v_add3_u32 v136, s94, v222, v224
	s_add_i32 s95, 0, 0x1ce00
	v_mov_b32_e32 v213, v23
	v_and_b32_e32 v214, 15, v213
	v_or_b32_e32 v215, s63, v214
	v_mul_lo_u32 v216, v215, s76
	v_ashrrev_i32_e32 v217, 4, v213
	v_lshlrev_b32_e32 v218, 3, v217
	v_add3_u32 v138, s95, v216, v218
	v_ashrrev_i32_e32 v219, 3, v213
	v_add_u32_e32 v220, s33, v219
	v_mul_lo_u32 v221, v220, s76
	v_lshlrev_b32_e32 v222, 4, v213
	v_and_b32_e32 v223, 0x70, v222
	v_add3_u32 v139, s48, v221, v223
	v_mov_b32_e32 v213, v23
	v_and_b32_e32 v214, 15, v213
	v_or_b32_e32 v215, s57, v214
	v_mul_u32_u24_e32 v216, 0x90, v215
	v_and_b32_e32 v217, -16, v213
	v_add3_u32 v140, s54, v216, v217
	v_or_b32_e32 v218, s60, v214
	v_mul_u32_u24_e32 v219, 0x90, v218
	v_add3_u32 v141, s54, v219, v217
	v_mul_u32_u24_e32 v220, 0x90, v214
	v_add_u32_e32 v221, 0x1200, v220
	v_add3_u32 v142, s55, v221, v217
	v_mov_b32_e32 v213, v23
	v_and_b32_e32 v214, 15, v213
	v_mul_u32_u24_e32 v215, 0x90, v214
	v_add_u32_e32 v216, 0x900, v215
	v_and_b32_e32 v217, -16, v213
	v_add3_u32 v143, s55, v216, v217
	v_or_b32_e32 v218, 16, v214
	v_mul_u32_u24_e32 v219, 0x90, v218
	v_add3_u32 v144, s55, v219, v217
	v_or_b32_e32 v220, 32, v214
	v_mul_u32_u24_e32 v221, 0x90, v220
	v_add3_u32 v145, s55, v221, v217
	v_mov_b32_e32 v213, v23
	v_and_b32_e32 v214, 15, v213
	v_or_b32_e32 v215, 48, v214
	v_mul_u32_u24_e32 v216, 0x90, v215
	v_and_b32_e32 v217, -16, v213
	v_add3_u32 v146, s55, v216, v217
	v_mul_lo_u32 v218, v213, s76
	v_add_u32_e32 v147, 0, v218
	v_lshlrev_b32_e32 v219, 2, v213
	v_add_u32_e32 v220, 0, v219
	v_add_u32_e32 v148, 0x12000, v220
	v_mov_b32_e32 v213, v23
	v_and_b32_e32 v214, 15, v213
	v_mul_u32_u24_e32 v215, 0x50, v214
	v_and_b32_e32 v216, -16, v213
	v_add3_u32 v217, 0, v215, v216
	v_add_u32_e32 v218, s59, v217
	v_add_u32_e32 v149, 0x14400, v218
	v_add_u32_e32 v150, 0x1e800, v218
	v_ashrrev_i32_e32 v219, 4, v213
	v_lshlrev_b32_e32 v220, 3, v219
	v_add_u32_e32 v221, s56, v220
	v_or_b32_e32 v222, s57, v214
	v_mul_u32_u24_e32 v223, 0x90, v222
	v_add_u32_e32 v151, v221, v223
	v_mov_b32_e32 v213, v23
	v_ashrrev_i32_e32 v214, 4, v213
	v_lshlrev_b32_e32 v215, 3, v214
	v_add_u32_e32 v216, s56, v215
	v_and_b32_e32 v217, 15, v213
	v_or_b32_e32 v218, s60, v217
	v_mul_u32_u24_e32 v219, 0x90, v218
	v_add_u32_e32 v152, v216, v219
	v_add_u32_e32 v220, s48, v215
	v_add_u32_e32 v221, s58, v220
	v_mul_u32_u24_e32 v222, 0x90, v217
	v_add_u32_e32 v223, 0x1200, v222
	v_add_u32_e32 v153, v221, v223
	v_mov_b32_e32 v213, v23
	v_ashrrev_i32_e32 v214, 4, v213
	v_lshlrev_b32_e32 v215, 3, v214
	v_add_u32_e32 v216, s48, v215
	v_add_u32_e32 v217, s58, v216
	v_and_b32_e32 v218, 15, v213
	v_mul_u32_u24_e32 v219, 0x90, v218
	v_add_u32_e32 v220, 0x900, v219
	v_add_u32_e32 v154, v217, v220
	v_mov_b32_e32 v213, v23
	v_ashrrev_i32_e32 v214, 4, v213
	v_lshlrev_b32_e32 v215, 3, v214
	v_add_u32_e32 v216, s48, v215
	v_add_u32_e32 v217, s58, v216
	v_and_b32_e32 v218, 15, v213
	v_mul_u32_u24_e32 v219, 0x90, v218
	v_add_u32_e32 v155, v217, v219
	v_mov_b32_e32 v220, s55
	v_mad_u32_u24 v221, v218, s76, v220
	v_and_b32_e32 v222, -16, v213
	v_add_u32_e32 v156, v221, v222
	v_mov_b32_e32 v213, v23
	v_lshlrev_b32_e32 v214, 2, v213
	v_add_u32_e32 v158, s49, v214
	v_mul_lo_u32 v215, v213, s76
	v_add_u32_e32 v159, s53, v215
	v_and_b32_e32 v160, -16, v213
	v_and_b32_e32 v161, 15, v213
	v_ashrrev_i32_e32 v162, 4, v213
	v_lshlrev_b32_e32 v216, 2, v162
	v_add_u32_e32 v217, 16, v216
	v_or_b32_e32 v218, s60, v161
	v_cmp_le_i32_e32 vcc, v217, v218
	s_nop 1
	v_cndmask_b32_e64 v219, 0, 1, vcc
	v_cmp_lt_i32_e32 vcc, v217, v218
	s_nop 1
	v_cndmask_b32_e64 v220, 0, 1, vcc
	v_cndmask_b32_e64 v221, v219, v220, s[20:21]
	v_and_b32_e32 v222, 1, v221
	v_cmp_eq_u32_e32 vcc, 1, v222
	s_nop 1
	v_cndmask_b32_e64 v163, 0, -1, vcc
	v_lshlrev_b32_e32 v213, 2, v162
	v_add_u32_e32 v214, 17, v213
	v_or_b32_e32 v215, s60, v161
	v_cmp_le_i32_e32 vcc, v214, v215
	s_nop 1
	v_cndmask_b32_e64 v216, 0, 1, vcc
	v_cmp_lt_i32_e32 vcc, v214, v215
	s_nop 1
	v_cndmask_b32_e64 v217, 0, 1, vcc
	v_cndmask_b32_e64 v218, v216, v217, s[20:21]
	v_and_b32_e32 v219, 1, v218
	v_cmp_eq_u32_e32 vcc, 1, v219
	s_nop 1
	v_cndmask_b32_e64 v164, 0, -1, vcc
	v_cmp_gt_i32_e32 vcc, 2, v162
	s_nop 1
	v_cndmask_b32_e64 v165, 0, -1, vcc
	v_or_b32_e32 v220, s57, v161
	v_or_b32_e32 v221, v213, v69
	v_cmp_gt_i32_e32 vcc, v220, v221
	s_nop 1
	v_cndmask_b32_e64 v166, 0, -1, vcc
	v_or_b32_e32 v213, s60, v161
	v_lshlrev_b32_e32 v214, 2, v162
	v_or_b32_e32 v215, v214, v69
	v_cmp_gt_i32_e32 vcc, v213, v215
	s_nop 1
	v_cndmask_b32_e64 v167, 0, -1, vcc
	v_add_u32_e32 v216, s57, v214
	v_cmp_le_i32_e32 vcc, v161, v216
	s_nop 1
	v_cndmask_b32_e64 v168, 0, -1, vcc
	v_or_b32_e32 v217, 16, v161
	v_cmp_le_i32_e32 vcc, v217, v216
	s_nop 1
	v_cndmask_b32_e64 v169, 0, -1, vcc
	v_or_b32_e32 v218, 32, v161
	v_cmp_le_i32_e32 vcc, v218, v216
	s_nop 1
	v_cndmask_b32_e64 v170, 0, -1, vcc
	v_add_u32_e32 v219, 13, v161
	v_cmp_lt_i32_e32 vcc, v219, v216
	s_nop 1
	v_cndmask_b32_e64 v171, 0, -1, vcc
	v_add_u32_e32 v220, 14, v161
	v_cmp_lt_i32_e32 vcc, v220, v216
	s_nop 1
	v_cndmask_b32_e64 v172, 0, -1, vcc
	v_lshlrev_b32_e32 v213, 2, v162
	v_add_u32_e32 v214, 16, v213
	v_cndmask_b32_e64 v215, 1, 0, s[20:21]
	v_or_b32_e32 v216, s57, v161
	v_add_u32_e32 v217, v215, v216
	v_cmp_lt_i32_e32 vcc, v214, v217
	s_nop 1
	v_cndmask_b32_e64 v173, 0, -1, vcc
	v_add_u32_e32 v218, 17, v213
	v_cmp_lt_i32_e32 vcc, v218, v217
	s_nop 1
	v_cndmask_b32_e64 v174, 0, -1, vcc
	v_add_u32_e32 v219, 18, v213
	v_cmp_lt_i32_e32 vcc, v219, v217
	s_nop 1
	v_cndmask_b32_e64 v175, 0, -1, vcc
	v_or_b32_e32 v220, s60, v161
	v_add_u32_e32 v221, v215, v220
	v_cmp_lt_i32_e32 vcc, v219, v221
	s_nop 1
	v_cndmask_b32_e64 v176, 0, -1, vcc
	v_lshlrev_b32_e32 v213, 2, v162
	v_add_u32_e32 v214, 19, v213
	v_cndmask_b32_e64 v215, 1, 0, s[20:21]
	v_or_b32_e32 v216, s57, v161
	v_add_u32_e32 v217, v215, v216
	v_cmp_lt_i32_e32 vcc, v214, v217
	s_nop 1
	v_cndmask_b32_e64 v177, 0, -1, vcc
	v_or_b32_e32 v218, s60, v161
	v_add_u32_e32 v219, v215, v218
	v_cmp_lt_i32_e32 vcc, v214, v219
	s_nop 1
	v_cndmask_b32_e64 v178, 0, -1, vcc
	v_add_u32_e32 v220, 29, v161
	v_add_u32_e32 v221, s57, v213
	v_cmp_lt_i32_e32 vcc, v220, v221
	s_nop 1
	v_cndmask_b32_e64 v179, 0, -1, vcc
	v_add_u32_e32 v213, 30, v161
	v_lshlrev_b32_e32 v214, 2, v162
	v_add_u32_e32 v215, s57, v214
	v_cmp_lt_i32_e32 vcc, v213, v215
	s_nop 1
	v_cndmask_b32_e64 v180, 0, -1, vcc
	v_add_u32_e32 v216, 32, v214
	v_cndmask_b32_e64 v217, 1, 0, s[20:21]
	v_or_b32_e32 v218, s57, v161
	v_add_u32_e32 v219, v217, v218
	v_cmp_lt_i32_e32 vcc, v216, v219
	s_nop 1
	v_cndmask_b32_e64 v181, 0, -1, vcc
	v_or_b32_e32 v220, s60, v161
	v_add_u32_e32 v221, v217, v220
	v_cmp_lt_i32_e32 vcc, v216, v221
	s_nop 1
	v_cndmask_b32_e64 v182, 0, -1, vcc
	v_lshlrev_b32_e32 v213, 2, v162
	v_add_u32_e32 v214, 33, v213
	v_cndmask_b32_e64 v215, 1, 0, s[20:21]
	v_or_b32_e32 v216, s57, v161
	v_add_u32_e32 v217, v215, v216
	v_cmp_lt_i32_e32 vcc, v214, v217
	s_nop 1
	v_cndmask_b32_e64 v183, 0, -1, vcc
	v_or_b32_e32 v218, s60, v161
	v_add_u32_e32 v219, v215, v218
	v_cmp_lt_i32_e32 vcc, v214, v219
	s_nop 1
	v_cndmask_b32_e64 v184, 0, -1, vcc
	v_add_u32_e32 v220, 34, v213
	v_cmp_lt_i32_e32 vcc, v220, v217
	s_nop 1
	v_cndmask_b32_e64 v185, 0, -1, vcc
	v_lshlrev_b32_e32 v213, 2, v162
	v_add_u32_e32 v214, 34, v213
	v_cndmask_b32_e64 v215, 1, 0, s[20:21]
	v_or_b32_e32 v216, s60, v161
	v_add_u32_e32 v217, v215, v216
	v_cmp_lt_i32_e32 vcc, v214, v217
	s_nop 1
	v_cndmask_b32_e64 v186, 0, -1, vcc
	v_add_u32_e32 v218, 35, v213
	v_or_b32_e32 v219, s57, v161
	v_add_u32_e32 v220, v215, v219
	v_cmp_lt_i32_e32 vcc, v218, v220
	s_nop 1
	v_cndmask_b32_e64 v187, 0, -1, vcc
	v_lshlrev_b32_e32 v213, 2, v162
	v_add_u32_e32 v214, 35, v213
	v_cndmask_b32_e64 v215, 1, 0, s[20:21]
	v_or_b32_e32 v216, s60, v161
	v_add_u32_e32 v217, v215, v216
	v_cmp_lt_i32_e32 vcc, v214, v217
	s_nop 1
	v_cndmask_b32_e64 v188, 0, -1, vcc
	v_add_u32_e32 v218, 48, v213
	v_cmp_lt_i32_e32 vcc, v218, v217
	s_nop 1
	v_cndmask_b32_e64 v189, 0, -1, vcc
	v_add_u32_e32 v219, 49, v213
	v_cmp_lt_i32_e32 vcc, v219, v217
	s_nop 1
	v_cndmask_b32_e64 v190, 0, -1, vcc
	v_add_u32_e32 v220, 50, v213
	v_cmp_lt_i32_e32 vcc, v220, v217
	s_nop 1
	v_cndmask_b32_e64 v191, 0, -1, vcc
	v_lshlrev_b32_e32 v213, 2, v162
	v_add_u32_e32 v214, 51, v213
	v_cndmask_b32_e64 v215, 1, 0, s[20:21]
	v_or_b32_e32 v216, s60, v161
	v_add_u32_e32 v217, v215, v216
	v_cmp_lt_i32_e32 vcc, v214, v217
	s_nop 1
	v_cndmask_b32_e64 v192, 0, -1, vcc
	v_add_u32_e32 v218, s57, v213
	v_cmp_lt_i32_e32 vcc, v161, v218
	s_nop 1
	v_cndmask_b32_e64 v193, 0, -1, vcc
	v_or_b32_e32 v219, 2, v218
	v_cmp_lt_i32_e32 vcc, v161, v219
	s_nop 1
	v_cndmask_b32_e64 v194, 0, -1, vcc
	v_or_b32_e32 v220, 3, v218
	v_cmp_lt_i32_e32 vcc, v161, v220
	s_nop 1
	v_cndmask_b32_e64 v195, 0, -1, vcc
	v_lshlrev_b32_e32 v213, 2, v162
	v_cndmask_b32_e64 v214, 1, 0, s[20:21]
	v_or_b32_e32 v215, s57, v161
	v_add_u32_e32 v216, v214, v215
	v_cmp_lt_i32_e32 vcc, v213, v216
	s_nop 1
	v_cndmask_b32_e64 v196, 0, -1, vcc
	v_or_b32_e32 v217, s60, v161
	v_add_u32_e32 v218, v214, v217
	v_cmp_lt_i32_e32 vcc, v213, v218
	s_nop 1
	v_cndmask_b32_e64 v197, 0, -1, vcc
	v_or_b32_e32 v219, 16, v161
	v_add_u32_e32 v220, s57, v213
	v_cmp_lt_i32_e32 vcc, v219, v220
	s_nop 1
	v_cndmask_b32_e64 v198, 0, -1, vcc
	v_lshlrev_b32_e32 v213, 2, v162
	v_or_b32_e32 v214, 2, v213
	v_cndmask_b32_e64 v215, 1, 0, s[20:21]
	v_or_b32_e32 v216, s57, v161
	v_add_u32_e32 v217, v215, v216
	v_cmp_lt_i32_e32 vcc, v214, v217
	s_nop 1
	v_cndmask_b32_e64 v199, 0, -1, vcc
	v_or_b32_e32 v218, s60, v161
	v_add_u32_e32 v219, v215, v218
	v_cmp_lt_i32_e32 vcc, v214, v219
	s_nop 1
	v_cndmask_b32_e64 v200, 0, -1, vcc
	v_or_b32_e32 v220, 32, v161
	v_add_u32_e32 v221, s57, v213
	v_cmp_lt_i32_e32 vcc, v220, v221
	s_nop 1
	v_cndmask_b32_e64 v201, 0, -1, vcc
	v_lshlrev_b32_e32 v213, 2, v162
	v_or_b32_e32 v214, 3, v213
	v_cndmask_b32_e64 v215, 1, 0, s[20:21]
	v_or_b32_e32 v216, s57, v161
	v_add_u32_e32 v217, v215, v216
	v_cmp_lt_i32_e32 vcc, v214, v217
	s_nop 1
	v_cndmask_b32_e64 v202, 0, -1, vcc
	v_or_b32_e32 v218, s60, v161
	v_add_u32_e32 v219, v215, v218
	v_cmp_lt_i32_e32 vcc, v214, v219
	s_nop 1
	v_cndmask_b32_e64 v203, 0, -1, vcc
	v_mov_b32_e32 v220, v23
	v_lshl_add_u32 v204, v220, 1, s74
	s_movk_i32 s96, 0x500
	v_mul_lo_u32 v213, v162, s96
	v_cmp_gt_i32_e32 vcc, 2, v162
	s_nop 1
	v_cndmask_b32_e32 v214, v80, v81, vcc
	v_add3_u32 v215, 0, v213, v214
	v_mov_b32_e32 v205, v215
	v_mov_b32_e32 v206, s16
	v_mov_b32_e32 v207, v23
	v_mul_u32_u24_e32 v208, 0x90, v161
	v_or_b32_e32 v209, 16, v161
	v_or_b32_e32 v210, 32, v161
	v_or_b32_e32 v211, 48, v161
	s_mov_b32 s96, 0x5040100
	s_mov_b32 s97, 0x7060302
	v_readlane_b32 s98, v233, 43
	v_readlane_b32 s99, v233, 44
	v_readlane_b32 s100, v233, 19
	v_readlane_b32 s101, v233, 20
	s_branch .LBB0_664

.LBB0_664:
	s_mov_b64 s[4:5], s[100:101]
	s_mov_b64 s[0:1], -1
	s_and_b64 vcc, exec, s[4:5]
	s_cbranch_vccz .LBB0_666
	v_cmp_lt_i64_e32 vcc, s[42:43], v[20:21]
	s_and_b64 s[0:1], vcc, exec
	s_cselect_b32 s4, s42, 0x1000
	s_mov_b64 s[0:1], 0

.LBB0_669:
	s_cmpk_lt_i32 s4, 0x1000
	s_mov_b64 s[0:1], -1
	s_cbranch_scc0 .LBB0_663
	s_mov_b64 s[4:5], s[100:101]
	s_and_b64 vcc, exec, s[4:5]
	s_cbranch_vccz .LBB0_672
	v_cmp_lt_i64_e32 vcc, s[42:43], v[20:21]
	s_and_b64 s[0:1], vcc, exec
	s_cselect_b32 s44, s42, 0x1000
	s_mov_b64 s[0:1], 0

.LBB0_675:
	s_mov_b64 s[4:5], s[100:101]
	s_mov_b64 s[0:1], -1
	s_and_b64 vcc, exec, s[4:5]
	s_cbranch_vccz .LBB0_677
	s_load_dword s0, s[82:83], 0x110
	v_readlane_b32 s1, v233, 38
	s_waitcnt lgkmcnt(0)
	s_add_u32 s0, s0, s42
	s_addc_u32 s1, s1, s43
	v_cmp_lt_i64_e32 vcc, s[0:1], v[20:21]
	s_and_b64 s[4:5], vcc, exec
	s_cselect_b32 s79, s0, 0x1000
	s_mov_b64 s[0:1], 0

.LBB0_698:
	v_cndmask_b32_e64 v29, v34, 0, s[24:25]
	v_readlane_b32 s80, v233, 39
	v_add_f32_e32 v34, v35, v29
	v_readlane_b32 s81, v233, 40
	v_readlane_b32 s0, v233, 41
	v_readlane_b32 s1, v233, 42
	v_cndmask_b32_e64 v29, v29, v34, s[80:81]
	v_add_f32_e32 v32, v32, v29
	v_cndmask_b32_e64 v29, v29, v32, s[0:1]
	s_mov_b64 s[0:1], s[98:99]
	v_add_f32_e32 v32, v33, v29
	s_nop 1
	v_cndmask_b32_e64 v29, v29, v32, s[0:1]
	v_readlane_b32 s0, v233, 45
	v_add_f32_e32 v30, v30, v29
	v_readlane_b32 s1, v233, 46
	s_nop 0
	s_nop 0
	v_cndmask_b32_e64 v29, v29, v30, s[0:1]
	v_readlane_b32 s0, v233, 47
	v_add_f32_e32 v31, v31, v29
	v_readlane_b32 s1, v233, 48
	s_nop 1
	v_cndmask_b32_e64 v29, v29, v31, s[0:1]
	v_add_f32_e32 v18, v18, v29
	s_nop 1
	s_nop 0
	v_readlane_b32 s0, v233, 49
	v_readlane_b32 s1, v233, 50
	s_nop 1
	v_cndmask_b32_e64 v18, v29, v18, s[0:1]
	v_readlane_b32 s0, v233, 51
	v_add_f32_e32 v19, v19, v18
	v_readlane_b32 s1, v233, 52
	s_nop 1
	v_cndmask_b32_e64 v18, v18, v19, s[0:1]
	v_rsq_f32_e32 v19, s46
	s_nop 0
	v_min_f32_e32 v19, 0x5368d4a5, v19
	s_nop 0
	v_mul_f32_e32 v19, v112, v19
	v_add_f32_e32 v109, v109, v18
	v_mul_f32_e32 v17, v19, v17
	v_rsq_f32_e32 v29, s19
	s_nop 0
	v_min_f32_e32 v29, 0x5368d4a5, v29
	s_nop 0
	v_mul_f32_e32 v29, v111, v29
	v_mul_f32_e32 v15, v29, v15
	s_nop 0
	v_rsq_f32_e32 v30, s18
	s_nop 0
	v_min_f32_e32 v30, 0x5368d4a5, v30
	s_nop 0
	v_mul_f32_e32 v114, v110, v30
	v_mul_f32_e32 v16, v114, v16
	s_nop 0
	v_rsq_f32_e32 v30, s17
	s_nop 0
	v_min_f32_e32 v30, 0x5368d4a5, v30
	s_nop 0
	v_mul_f32_e32 v104, v104, v30
	v_mul_f32_e32 v14, v104, v14
	s_nop 0
	v_rsq_f32_e32 v30, s9
	s_nop 0
	v_min_f32_e32 v30, 0x5368d4a5, v30
	s_nop 0
	v_mul_f32_e32 v100, v100, v30
	v_mul_f32_e32 v13, v100, v13
	s_nop 0
	v_rsq_f32_e32 v30, s8
	s_nop 0
	v_min_f32_e32 v30, 0x5368d4a5, v30
	s_nop 0
	v_mul_f32_e32 v115, v99, v30
	v_lshlrev_b32_e32 v110, 16, v61
	v_mul_f32_e32 v11, v115, v11
	s_nop 0
	v_and_b32_e32 v31, 0xffff0000, v88
	v_rsq_f32_e32 v30, s7
	s_nop 0
	v_min_f32_e32 v30, 0x5368d4a5, v30
	s_nop 0
	v_mul_f32_e32 v116, v98, v30
	v_lshlrev_b32_e32 v30, 16, v88
	v_lshlrev_b32_e32 v33, 16, v54
	v_lshlrev_b32_e32 v35, 16, v52
	v_lshlrev_b32_e32 v34, 16, v45
	v_mov_b32_e32 v32, v31
	v_pk_add_f32 v[30:31], v[30:31], v[34:35] neg_lo:[0,1] neg_hi:[0,1]
	v_pk_add_f32 v[98:99], v[34:35], v[32:33] neg_lo:[0,1] neg_hi:[0,1]
	v_pk_fma_f32 v[30:31], v[24:25], v[30:31], v[34:35] op_sel_hi:[0,1,1]
	v_pk_fma_f32 v[34:35], v[98:99], v[24:25], v[32:33] op_sel_hi:[1,0,1]
	v_lshlrev_b32_e32 v99, 16, v66
	v_lshlrev_b32_e32 v98, 16, v56
	v_lshlrev_b32_e32 v111, 16, v71
	v_pk_mov_b32 v[32:33], v[32:33], v[110:111] op_sel:[1,0]
	v_mul_f32_e32 v12, v116, v12
	v_pk_add_f32 v[32:33], v[32:33], v[98:99] neg_lo:[0,1] neg_hi:[0,1]
	v_pk_fma_f32 v[32:33], v[32:33], v[24:25], v[98:99] op_sel_hi:[1,0,1]
	s_nop 0
	s_nop 1
	v_pk_add_f32 v[112:113], v[98:99], v[110:111] neg_lo:[0,1] neg_hi:[0,1]
	s_nop 0
	v_pk_fma_f32 v[98:99], v[112:113], v[24:25], v[110:111] op_sel_hi:[1,0,1]
	v_rsq_f32_e32 v110, s6
	s_nop 0
	v_min_f32_e32 v110, 0x5368d4a5, v110
	s_nop 0
	v_mul_f32_e32 v97, v97, v110
	v_mul_f32_e32 v110, 0x3fb8aa3b, v18
	v_exp_f32_e32 v111, v110
	v_mul_f32_e32 v110, 0x3fb8aa3b, v109
	v_exp_f32_e32 v112, v110
	v_exp_f32_e64 v110, -v110
	v_mul_f32_e32 v10, v97, v10
	v_mul_f32_e64 v97, v111, -v97
	v_mul_f32_e32 v96, v96, v112
	v_cvt_pk_bf16_f32 v109, v97, s0
	v_cvt_pk_bf16_f32 v96, v96, s0
	v_mul_f32_e32 v97, v10, v110
	v_mul_f32_e32 v111, v0, v110
	v_cvt_pk_bf16_f32 v113, v30, v31
	v_add_f32_e32 v31, v108, v18
	v_cvt_pk_bf16_f32 v97, v97, s0
	v_cvt_pk_bf16_f32 v111, v111, s0
	ds_write_b16 v204, v109
	ds_write_b16 v204, v96 offset:9216
	ds_write_b16 v204, v97 offset:18432
	ds_write_b16 v204, v111 offset:27648
	v_mul_f32_e32 v96, 0x3fb8aa3b, v31
	v_exp_f32_e32 v97, v96
	v_exp_f32_e64 v96, -v96
	v_mul_f32_e64 v31, v112, -v116
	v_cvt_pk_bf16_f32 v112, v34, v35
	v_add_f32_e32 v34, v107, v18
	v_mul_f32_e32 v111, v4, v96
	v_mul_f32_e32 v35, 0x3fb8aa3b, v34
	v_cvt_pk_bf16_f32 v31, v31, s0
	v_mul_f32_e32 v94, v94, v97
	v_mul_f32_e32 v108, v12, v96
	v_cvt_pk_bf16_f32 v111, v111, s0
	v_exp_f32_e32 v35, v35
	v_mul_f32_e32 v34, 0xbfb8aa3b, v34
	v_cvt_pk_bf16_f32 v94, v94, s0
	v_cvt_pk_bf16_f32 v108, v108, s0
	ds_write_b16 v204, v31 offset:144
	ds_write_b16 v204, v94 offset:9360
	ds_write_b16 v204, v108 offset:18576
	ds_write_b16 v204, v111 offset:27792
	v_exp_f32_e32 v111, v34
	v_mul_f32_e64 v34, v97, -v115
	v_cvt_pk_bf16_f32 v94, v34, s0
	v_mul_f32_e32 v34, v92, v35
	v_cvt_pk_bf16_f32 v34, v34, s0
	v_mul_f32_e32 v92, v11, v111
	v_mul_f32_e32 v97, v1, v111
	v_cvt_pk_bf16_f32 v92, v92, s0
	v_cvt_pk_bf16_f32 v97, v97, s0
	ds_write_b16 v204, v94 offset:288
	ds_write_b16 v204, v34 offset:9504
	ds_write_b16 v204, v92 offset:18720
	ds_write_b16 v204, v97 offset:27936
	v_add_f32_e32 v34, v106, v18
	v_mul_f32_e32 v92, 0x3fb8aa3b, v34
	v_exp_f32_e64 v97, -v92
	v_exp_f32_e32 v92, v92
	v_mul_f32_e64 v34, v35, -v100
	v_cvt_pk_bf16_f32 v100, v34, s0
	v_mul_f32_e32 v34, v90, v92
	v_cvt_pk_bf16_f32 v34, v34, s0
	v_mul_f32_e32 v35, v13, v97
	v_mul_f32_e32 v90, v5, v97
	v_cvt_pk_bf16_f32 v35, v35, s0
	v_cvt_pk_bf16_f32 v90, v90, s0
	ds_write_b16 v204, v100 offset:432
	ds_write_b16 v204, v34 offset:9648
	ds_write_b16 v204, v35 offset:18864
	ds_write_b16 v204, v90 offset:28080
	v_add_f32_e32 v34, v105, v18
	v_mul_f32_e32 v35, 0x3fb8aa3b, v34
	v_exp_f32_e64 v34, -v35
	v_exp_f32_e32 v35, v35
	v_mul_f32_e64 v90, v92, -v104
	v_cvt_pk_bf16_f32 v105, v32, v33
	v_add_f32_e32 v32, v103, v18
	v_cvt_pk_bf16_f32 v92, v90, s0
	v_mul_f32_e32 v90, v95, v35
	v_mul_f32_e32 v33, 0x3fb8aa3b, v32
	v_cvt_pk_bf16_f32 v90, v90, s0
	v_mul_f32_e32 v95, v14, v34
	v_mul_f32_e32 v104, v6, v34
	v_exp_f32_e32 v33, v33
	v_mul_f32_e32 v32, 0xbfb8aa3b, v32
	v_cvt_pk_bf16_f32 v95, v95, s0
	v_cvt_pk_bf16_f32 v104, v104, s0
	ds_write_b16 v204, v92 offset:576
	ds_write_b16 v204, v90 offset:9792
	ds_write_b16 v204, v95 offset:19008
	ds_write_b16 v204, v104 offset:28224
	v_exp_f32_e32 v90, v32
	v_mul_f32_e64 v32, v35, -v114
	v_mul_f32_e32 v35, v93, v33
	v_cvt_pk_bf16_f32 v32, v32, s0
	v_cvt_pk_bf16_f32 v35, v35, s0
	v_mul_f32_e32 v93, v16, v90
	v_mul_f32_e32 v95, v8, v90
	v_cvt_pk_bf16_f32 v93, v93, s0
	v_cvt_pk_bf16_f32 v95, v95, s0
	ds_write_b16 v204, v32 offset:720
	ds_write_b16 v204, v35 offset:9936
	ds_write_b16 v204, v93 offset:19152
	ds_write_b16 v204, v95 offset:28368
	v_add_f32_e32 v35, v102, v18
	v_mul_f32_e32 v93, 0x3fb8aa3b, v35
	v_exp_f32_e64 v35, -v93
	v_exp_f32_e32 v93, v93
	v_mul_f32_e64 v29, v33, -v29
	v_mul_f32_e32 v33, v91, v93
	v_cvt_pk_bf16_f32 v29, v29, s0
	v_cvt_pk_bf16_f32 v33, v33, s0
	v_mul_f32_e32 v91, v15, v35
	v_mul_f32_e32 v95, v7, v35
	v_add_f32_e32 v18, v101, v18
	v_cvt_pk_bf16_f32 v91, v91, s0
	v_cvt_pk_bf16_f32 v95, v95, s0
	ds_write_b16 v204, v29 offset:864
	ds_write_b16 v204, v33 offset:10080
	ds_write_b16 v204, v91 offset:19296
	ds_write_b16 v204, v95 offset:28512
	v_mul_f32_e32 v33, 0x3fb8aa3b, v18
	v_exp_f32_e64 v91, -v33
	v_exp_f32_e32 v33, v33
	v_mul_f32_e64 v18, v93, -v19
	v_mul_f32_e32 v19, v89, v33
	v_cvt_pk_bf16_f32 v18, v18, s0
	v_cvt_pk_bf16_f32 v19, v19, s0
	v_mul_f32_e32 v33, v17, v91
	v_mul_f32_e32 v89, v9, v91
	v_cvt_pk_bf16_f32 v33, v33, s0
	v_cvt_pk_bf16_f32 v89, v89, s0
	ds_write_b16 v204, v18 offset:1008
	ds_write_b16 v204, v19 offset:10224
	ds_write_b16 v204, v33 offset:19440
	ds_write_b16 v204, v89 offset:28656
	v_perm_b32 v30, v31, v109, s96
	v_perm_b32 v31, v100, v94, s96
	v_perm_b32 v33, v18, v29, s96
	v_perm_b32 v32, v32, v92, s96
	v_pk_mul_f32 v[18:19], v[2:3], v[110:111] op_sel_hi:[0,1]
	ds_write_b128 v159, v[30:33] offset:36864
	v_pk_mul_f32 v[30:31], v[2:3], v[96:97] op_sel_hi:[0,1]
	v_pk_mul_f32 v[10:11], v[10:11], v[18:19]
	v_pk_mul_f32 v[0:1], v[0:1], v[18:19]
	v_cvt_pk_bf16_f32 v32, v10, v11
	v_pk_mul_f32 v[10:11], v[12:13], v[30:31]
	v_cvt_pk_bf16_f32 v98, v98, v99
	v_cvt_pk_bf16_f32 v10, v10, v11
	v_perm_b32 v11, v10, v32, s97
	v_perm_b32 v10, v10, v32, s96
	v_pk_mul_f32 v[32:33], v[2:3], v[34:35] op_sel_hi:[0,1]
	v_pk_mul_f32 v[34:35], v[2:3], v[90:91] op_sel_hi:[0,1]
	v_pk_mul_f32 v[12:13], v[14:15], v[32:33]
	s_mov_b64 s[0:1], -1
	v_cvt_pk_bf16_f32 v2, v12, v13
	v_pk_mul_f32 v[12:13], v[16:17], v[34:35]
	s_and_b64 vcc, exec, s[80:81]
	v_cvt_pk_bf16_f32 v12, v12, v13
	v_perm_b32 v13, v12, v2, s97
	v_perm_b32 v12, v12, v2, s96
	v_cvt_pk_bf16_f32 v2, v0, v1
	v_pk_mul_f32 v[0:1], v[4:5], v[30:31]
	ds_write_b128 v159, v[10:13] offset:46080
	v_cvt_pk_bf16_f32 v0, v0, v1
	v_perm_b32 v5, v0, v2, s97
	v_perm_b32 v4, v0, v2, s96
	v_pk_mul_f32 v[0:1], v[6:7], v[32:33]
	v_mov_b32_e32 v12, s55
	v_cvt_pk_bf16_f32 v2, v0, v1
	v_pk_mul_f32 v[0:1], v[8:9], v[34:35]
	s_nop 0
	v_cvt_pk_bf16_f32 v0, v0, v1
	v_perm_b32 v7, v0, v2, s97
	v_perm_b32 v6, v0, v2, s96
	ds_write_b128 v159, v[4:7] offset:55296
	v_perm_b32 v5, v112, v113, s97
	v_perm_b32 v4, v112, v113, s96
	v_perm_b32 v7, v98, v105, s97
	v_perm_b32 v6, v98, v105, s96
	ds_write_b128 v159, v[4:7] offset:64512
	s_waitcnt lgkmcnt(0)
	s_barrier
	s_nop 0
	v_and_b32_e32 v0, 15, v28
	v_and_b32_e32 v1, -16, v28
	v_mad_u32_u24 v12, v0, s76, v12
	v_add_u32_e32 v30, v12, v1
	ds_read_b128 v[8:11], v140
	ds_read_b128 v[4:7], v140 offset:64
	ds_read_b128 v[16:19], v156
	ds_read_b128 v[12:15], v156 offset:64
	v_ashrrev_i32_e32 v2, 4, v28
	v_lshlrev_b32_e32 v29, 2, v2
	v_lshlrev_b32_e32 v2, 3, v2
	v_or_b32_e32 v89, v29, v69
	s_cbranch_vccz .LBB0_700
	s_waitcnt lgkmcnt(1)
	v_mfma_f32_16x16x32_bf16 v[94:97], v[16:19], v[8:11], 0
	s_mov_b64 s[0:1], 0
	s_waitcnt lgkmcnt(0)
	v_mfma_f32_16x16x32_bf16 v[94:97], v[12:15], v[4:7], v[94:97]
	s_nop 7
	v_bfi_b32 v35, v196, v94, v206
	v_and_b32_e32 v90, v166, v95
	v_cvt_pk_bf16_f32 v90, v35, v90
	v_and_b32_e32 v91, v199, v96
	v_and_b32_e32 v93, v202, v97
	v_cvt_pk_bf16_f32 v91, v91, v93
	ds_write_b64 v151, v[90:91]

.LBB0_703:
	v_readlane_b32 s0, v233, 39
	v_readlane_b32 s1, v233, 40
	s_mov_b64 s[6:7], -1
	s_andn2_b64 vcc, exec, s[0:1]
	s_waitcnt lgkmcnt(0)
	v_cndmask_b32_e64 v12, 0, 1, s[0:1]
	v_cmp_ne_u32_e64 s[4:5], 1, v12
	v_cndmask_b32_e64 v12, 0, 1, s[34:35]
	v_cmp_ne_u32_e64 s[0:1], 1, v12
	s_cbranch_vccnz .LBB0_711
	s_and_b64 vcc, exec, s[0:1]
	s_cbranch_vccnz .Lpa_z0
	ds_read_b128 v[12:15], v156 offset:2304
	ds_read_b128 v[16:19], v156 offset:2368
	s_waitcnt lgkmcnt(1)
	v_mfma_f32_16x16x32_bf16 v[12:15], v[12:15], v[8:11], 0
	s_waitcnt lgkmcnt(0)
	v_mfma_f32_16x16x32_bf16 v[12:15], v[16:19], v[4:7], v[12:15]

.LBB0_708:
	s_and_b64 vcc, exec, s[0:1]
	s_cbranch_vccnz .Lpa_z1
	ds_read_b128 v[12:15], v156 offset:4608
	ds_read_b128 v[16:19], v156 offset:4672
	s_waitcnt lgkmcnt(1)
	v_mfma_f32_16x16x32_bf16 v[12:15], v[12:15], v[8:11], 0
	s_waitcnt lgkmcnt(0)
	v_mfma_f32_16x16x32_bf16 v[12:15], v[16:19], v[4:7], v[12:15]

.LBB0_711:
	s_and_b64 vcc, exec, s[6:7]
	s_cbranch_vccz .LBB0_707
	s_and_b64 vcc, exec, s[0:1]
	s_cbranch_vccnz .Lpa_z2
	ds_read_b128 v[12:15], v143
	ds_read_b128 v[96:99], v143 offset:64
	s_waitcnt lgkmcnt(1)
	v_mfma_f32_16x16x32_bf16 v[12:15], v[8:11], v[12:15], 0
	s_waitcnt lgkmcnt(0)
	v_mfma_f32_16x16x32_bf16 v[12:15], v[4:7], v[96:99], v[12:15]

.LBB0_715:
	s_and_b64 vcc, exec, s[6:7]
	s_cbranch_vccz .LBB0_720
	s_and_b64 vcc, exec, s[0:1]
	s_cbranch_vccnz .Lpa_z3
	ds_read_b128 v[12:15], v142
	ds_read_b128 v[96:99], v142 offset:64
	s_waitcnt lgkmcnt(1)
	v_mfma_f32_16x16x32_bf16 v[8:11], v[8:11], v[12:15], 0
	s_waitcnt lgkmcnt(0)
	v_mfma_f32_16x16x32_bf16 v[12:15], v[4:7], v[96:99], v[8:11]

.LBB0_733:
	s_and_b64 vcc, exec, s[4:5]
	s_mov_b64 s[6:7], -1
	s_cbranch_vccnz .LBB0_741
	s_waitcnt lgkmcnt(0)
	s_and_b64 vcc, exec, s[0:1]
	s_cbranch_vccnz .Lpa_z4
	ds_read_b128 v[12:15], v156 offset:4608
	ds_read_b128 v[16:19], v156 offset:4672
	s_waitcnt lgkmcnt(1)
	v_mfma_f32_16x16x32_bf16 v[12:15], v[12:15], v[8:11], 0
	s_waitcnt lgkmcnt(0)
	v_mfma_f32_16x16x32_bf16 v[12:15], v[16:19], v[4:7], v[12:15]

.LBB0_738:
	s_waitcnt lgkmcnt(0)
	s_and_b64 vcc, exec, s[0:1]
	s_cbranch_vccnz .Lpa_z5
	ds_read_b128 v[12:15], v156 offset:6912
	ds_read_b128 v[16:19], v156 offset:6976
	s_waitcnt lgkmcnt(1)
	v_mfma_f32_16x16x32_bf16 v[12:15], v[12:15], v[8:11], 0
	s_waitcnt lgkmcnt(0)
	v_mfma_f32_16x16x32_bf16 v[12:15], v[16:19], v[4:7], v[12:15]

.LBB0_741:
	s_and_b64 vcc, exec, s[6:7]
	s_cbranch_vccz .LBB0_737
	s_waitcnt lgkmcnt(1)
	v_or_b32_e32 v17, 32, v0
	v_mul_u32_u24_e32 v16, 0x90, v17
	s_waitcnt lgkmcnt(0)
	s_and_b64 vcc, exec, s[0:1]
	s_cbranch_vccnz .Lpa_z6
	v_add3_u32 v18, s55, v16, v1
	ds_read_b128 v[12:15], v145
	ds_read_b128 v[90:93], v145 offset:64
	s_waitcnt lgkmcnt(1)
	v_mfma_f32_16x16x32_bf16 v[12:15], v[8:11], v[12:15], 0
	s_waitcnt lgkmcnt(0)
	v_mfma_f32_16x16x32_bf16 v[12:15], v[4:7], v[90:93], v[12:15]

.LBB0_745:
	s_and_b64 vcc, exec, s[4:5]
	s_cbranch_vccz .LBB0_750
	s_waitcnt lgkmcnt(1)
	v_or_b32_e32 v17, 48, v0
	v_mul_u32_u24_e32 v16, 0x90, v17
	s_waitcnt lgkmcnt(0)
	s_and_b64 vcc, exec, s[0:1]
	s_cbranch_vccnz .Lpa_z7
	ds_read_b128 v[12:15], v146
	ds_read_b128 v[90:93], v146 offset:64
	s_waitcnt lgkmcnt(1)
	v_mfma_f32_16x16x32_bf16 v[8:11], v[8:11], v[12:15], 0
	s_waitcnt lgkmcnt(0)
	v_mfma_f32_16x16x32_bf16 v[12:15], v[4:7], v[90:93], v[8:11]

.LBB0_750:
	v_cndmask_b32_e64 v2, 0, 1, s[26:27]
	s_waitcnt lgkmcnt(0)
	s_barrier
	v_cmp_ne_u32_e64 s[0:1], 1, v2
	v_and_b32_e32 v0, 15, v28
	v_ashrrev_i32_e32 v1, 4, v28
	s_andn2_b64 vcc, exec, s[26:27]
	s_mov_b64 s[4:5], -1
	s_cbranch_vccnz .LBB0_764
	s_and_b64 vcc, exec, s[36:37]
	s_cbranch_vccz .LBB0_755
	s_mov_b64 s[4:5], s[98:99]
	s_andn2_b64 vcc, exec, s[4:5]
	s_cbranch_vccnz .LBB0_754
	v_and_b32_e32 v8, -16, v28
	v_mul_u32_u24_e32 v4, 0x90, v0
	s_add_i32 s4, 0, 0x14e00
	v_add3_u32 v29, s4, v4, v8
	ds_read_b128 v[4:7], v134
	v_or_b32_e32 v2, s63, v0
	v_mul_lo_u32 v2, v2, s76
	ds_read_b128 v[8:11], v134 offset:64
	ds_read_b128 v[12:15], v132 offset:64512
	ds_read_b128 v[16:19], v132 offset:64576
	s_add_i32 s4, 0, 0x1ce00
	v_lshlrev_b32_e32 v30, 3, v1
	s_waitcnt lgkmcnt(1)
	v_mfma_f32_16x16x32_bf16 v[4:7], v[4:7], v[12:15], 0
	v_add3_u32 v2, s4, v2, v30
	s_waitcnt lgkmcnt(0)
	v_mfma_f32_16x16x32_bf16 v[4:7], v[8:11], v[16:19], v[4:7]
	s_nop 7
	v_cvt_pk_bf16_f32 v4, v4, v5
	v_cvt_pk_bf16_f32 v5, v6, v7
	ds_write_b64 v138, v[4:5]
	ds_read_b128 v[4:7], v134 offset:2304
	ds_read_b128 v[8:11], v134 offset:2368
	s_waitcnt lgkmcnt(1)
	v_mfma_f32_16x16x32_bf16 v[4:7], v[4:7], v[12:15], 0
	s_waitcnt lgkmcnt(0)
	v_mfma_f32_16x16x32_bf16 v[4:7], v[8:11], v[16:19], v[4:7]
	s_nop 7
	v_cvt_pk_bf16_f32 v4, v4, v5
	v_cvt_pk_bf16_f32 v5, v6, v7
	ds_write_b64 v138, v[4:5] offset:32
	ds_read_b128 v[4:7], v134 offset:4608
	ds_read_b128 v[8:11], v134 offset:4672
	s_waitcnt lgkmcnt(1)
	v_mfma_f32_16x16x32_bf16 v[4:7], v[4:7], v[12:15], 0
	s_waitcnt lgkmcnt(0)
	v_mfma_f32_16x16x32_bf16 v[4:7], v[8:11], v[16:19], v[4:7]
	s_nop 7
	v_cvt_pk_bf16_f32 v4, v4, v5
	v_cvt_pk_bf16_f32 v5, v6, v7
	ds_write_b64 v138, v[4:5] offset:64
	ds_read_b128 v[4:7], v134 offset:6912
	ds_read_b128 v[8:11], v134 offset:6976
	s_waitcnt lgkmcnt(1)
	v_mfma_f32_16x16x32_bf16 v[4:7], v[4:7], v[12:15], 0
	s_waitcnt lgkmcnt(0)
	v_mfma_f32_16x16x32_bf16 v[4:7], v[8:11], v[16:19], v[4:7]
	s_nop 7
	v_cvt_pk_bf16_f32 v4, v4, v5
	v_cvt_pk_bf16_f32 v5, v6, v7
	ds_write_b64 v138, v[4:5] offset:96

.LBB0_789:
	v_and_b32_e32 v0, 15, v207
	v_or_b32_e32 v1, s68, v0
	v_and_b32_e32 v2, -16, v207
	v_mul_u32_u24_e32 v0, 0x90, v0
	v_add3_u32 v29, 0, v0, v2
	ds_read_b128 v[4:7], v29
	v_mul_u32_u24_e32 v0, 0x90, v1
	v_add3_u32 v1, s66, v0, v2
	ds_read_b128 v[8:11], v29 offset:64
	ds_read_b128 v[12:15], v1
	ds_read_b128 v[16:19], v1 offset:64
	v_ashrrev_i32_e32 v1, 1, v207
	v_and_b32_e32 v1, -8, v1
	v_add3_u32 v2, s67, v0, v1
	s_waitcnt lgkmcnt(1)
	v_mfma_f32_16x16x32_bf16 v[4:7], v[4:7], v[12:15], 0
	s_mov_b64 s[4:5], s[98:99]
	s_mov_b64 s[0:1], -1
	s_waitcnt lgkmcnt(0)
	v_mfma_f32_16x16x32_bf16 v[4:7], v[8:11], v[16:19], v[4:7]
	s_and_b64 vcc, exec, s[4:5]
	s_nop 6
	v_cvt_pk_bf16_f32 v0, v4, v5
	v_cvt_pk_bf16_f32 v1, v6, v7
	ds_write_b64 v2, v[0:1]
	ds_read_b128 v[4:7], v29 offset:2304
	ds_read_b128 v[8:11], v29 offset:2368
	s_waitcnt lgkmcnt(1)
	v_mfma_f32_16x16x32_bf16 v[4:7], v[4:7], v[12:15], 0
	s_waitcnt lgkmcnt(0)
	v_mfma_f32_16x16x32_bf16 v[4:7], v[8:11], v[16:19], v[4:7]
	s_nop 7
	v_cvt_pk_bf16_f32 v0, v4, v5
	v_cvt_pk_bf16_f32 v1, v6, v7
	ds_write_b64 v2, v[0:1] offset:32
	ds_read_b128 v[4:7], v29 offset:4608
	ds_read_b128 v[8:11], v29 offset:4672
	s_waitcnt lgkmcnt(1)
	v_mfma_f32_16x16x32_bf16 v[4:7], v[4:7], v[12:15], 0
	s_waitcnt lgkmcnt(0)
	v_mfma_f32_16x16x32_bf16 v[4:7], v[8:11], v[16:19], v[4:7]
	s_nop 7
	v_cvt_pk_bf16_f32 v0, v4, v5
	v_cvt_pk_bf16_f32 v1, v6, v7
	ds_write_b64 v2, v[0:1] offset:64
	ds_read_b128 v[4:7], v29 offset:6912
	ds_read_b128 v[8:11], v29 offset:6976
	s_waitcnt lgkmcnt(1)
	v_mfma_f32_16x16x32_bf16 v[4:7], v[4:7], v[12:15], 0
	s_waitcnt lgkmcnt(0)
	v_mfma_f32_16x16x32_bf16 v[4:7], v[8:11], v[16:19], v[4:7]
	s_nop 7
	v_cvt_pk_bf16_f32 v0, v4, v5
	v_cvt_pk_bf16_f32 v1, v6, v7
	ds_write_b64 v2, v[0:1] offset:96
	s_waitcnt lgkmcnt(0)
	s_barrier
	s_nop 0
	v_and_b32_e32 v7, 15, v207
	v_ashrrev_i32_e32 v1, 4, v207
	v_and_b32_e32 v0, -16, v207
	v_lshlrev_b32_e32 v5, 3, v1
	v_mul_u32_u24_e32 v6, 0x90, v7
	v_mad_u32_u24 v4, v7, s76, v82
	v_mad_u32_u24 v2, v7, s76, v83
	v_mad_u32_u24 v1, v7, s76, v87
	s_cbranch_vccz .LBB0_791
	v_or_b32_e32 v8, s63, v7
	v_mul_lo_u32 v8, v8, s76
	v_add_u32_e32 v89, s69, v5
	v_add3_u32 v29, 0, v8, v0
	v_add3_u32 v30, 0, v89, v6
	ds_read_b128 v[8:11], v29 offset:18432
	ds_read_b128 v[12:15], v29 offset:18496
	ds_read_b64 v[32:33], v30 offset:9216
	s_add_i32 s0, 0, 0x17200
	v_add_u32_e32 v98, s0, v0
	v_mad_u32_u24 v99, v7, s76, v98
	ds_read_b128 v[16:19], v99
	ds_read_b64 v[34:35], v30 offset:11520
	ds_read_b64 v[94:95], v30 offset:13824
	ds_read_b64 v[96:97], v30 offset:16128
	s_waitcnt lgkmcnt(4)
	v_lshlrev_b32_e32 v30, 16, v32
	v_and_b32_e32 v31, 0xffff0000, v32
	v_lshlrev_b32_e32 v32, 16, v33
	v_and_b32_e32 v33, 0xffff0000, v33
	ds_read_b128 v[90:93], v99 offset:64
	s_add_i32 s1, 0, 0x14e00
	s_waitcnt lgkmcnt(4)
	v_mfma_f32_16x16x32_bf16 v[16:19], v[8:11], v[16:19], v[30:33]
	v_add3_u32 v89, s1, v89, v6
	v_add_u32_e32 v102, v98, v4
	v_add3_u32 v103, s0, v4, v0
	s_waitcnt lgkmcnt(0)
	v_mfma_f32_16x16x32_bf16 v[16:19], v[12:15], v[90:93], v[16:19]
	v_lshlrev_b32_e32 v30, 16, v34
	v_and_b32_e32 v31, 0xffff0000, v34
	v_lshlrev_b32_e32 v32, 16, v35
	v_and_b32_e32 v33, 0xffff0000, v35
	v_add_u32_e32 v34, v98, v2
	s_nop 2
	v_cvt_pk_bf16_f32 v16, v16, v17
	v_cvt_pk_bf16_f32 v17, v18, v19
	ds_write_b64 v89, v[16:17]
	ds_read_b128 v[16:19], v102
	ds_read_b128 v[90:93], v103 offset:64
	s_waitcnt lgkmcnt(1)
	v_mfma_f32_16x16x32_bf16 v[16:19], v[8:11], v[16:19], v[30:33]
	v_add3_u32 v35, s0, v2, v0
	s_nop 1
	v_lshlrev_b32_e32 v30, 16, v94
	v_and_b32_e32 v31, 0xffff0000, v94
	s_waitcnt lgkmcnt(0)
	v_mfma_f32_16x16x32_bf16 v[16:19], v[12:15], v[90:93], v[16:19]
	v_lshlrev_b32_e32 v32, 16, v95
	v_and_b32_e32 v33, 0xffff0000, v95
	v_add_u32_e32 v104, v98, v1
	v_add3_u32 v105, s0, v1, v0
	s_add_i32 s0, 0, 0x19600
	s_nop 2
	v_cvt_pk_bf16_f32 v16, v16, v17
	v_cvt_pk_bf16_f32 v17, v18, v19
	ds_write_b64 v89, v[16:17] offset:2304
	ds_read_b128 v[16:19], v34
	ds_read_b128 v[90:93], v35 offset:64
	s_waitcnt lgkmcnt(1)
	v_mfma_f32_16x16x32_bf16 v[16:19], v[8:11], v[16:19], v[30:33]
	s_nop 2
	v_lshlrev_b32_e32 v30, 16, v96
	v_and_b32_e32 v31, 0xffff0000, v96
	v_lshlrev_b32_e32 v32, 16, v97
	s_waitcnt lgkmcnt(0)
	v_mfma_f32_16x16x32_bf16 v[16:19], v[12:15], v[90:93], v[16:19]
	v_and_b32_e32 v33, 0xffff0000, v97
	s_nop 6
	v_cvt_pk_bf16_f32 v16, v16, v17
	v_cvt_pk_bf16_f32 v17, v18, v19
	ds_write_b64 v89, v[16:17] offset:4608
	ds_read_b128 v[16:19], v104
	ds_read_b128 v[90:93], v105 offset:64
	s_waitcnt lgkmcnt(1)
	v_mfma_f32_16x16x32_bf16 v[8:11], v[8:11], v[16:19], v[30:33]
	s_waitcnt lgkmcnt(0)
	v_mfma_f32_16x16x32_bf16 v[8:11], v[12:15], v[90:93], v[8:11]
	s_nop 7
	v_cvt_pk_bf16_f32 v8, v8, v9
	v_cvt_pk_bf16_f32 v9, v10, v11
	ds_write_b64 v89, v[8:9] offset:6912
	ds_read_b128 v[8:11], v29 offset:27648
	ds_read_b128 v[12:15], v29 offset:27712
	ds_read_b128 v[16:19], v99
	ds_read_b128 v[30:33], v99 offset:64
	ds_read_b128 v[90:93], v29 offset:64512
	ds_read_b128 v[94:97], v29 offset:64576
	s_waitcnt lgkmcnt(3)
	v_mfma_f32_16x16x32_bf16 v[16:19], v[8:11], v[16:19], 0
	v_add_u32_e32 v89, s0, v0
	v_mad_u32_u24 v98, v7, s76, v89
	v_add3_u32 v29, s70, v5, v6
	s_waitcnt lgkmcnt(2)
	v_mfma_f32_16x16x32_bf16 v[16:19], v[12:15], v[30:33], v[16:19]
	ds_read_b128 v[30:33], v98
	ds_read_b128 v[98:101], v98 offset:64
	s_waitcnt lgkmcnt(1)
	v_mfma_f32_16x16x32_bf16 v[16:19], v[90:93], v[30:33], v[16:19]
	s_waitcnt lgkmcnt(0)
	v_mfma_f32_16x16x32_bf16 v[16:19], v[94:97], v[98:101], v[16:19]
	v_add_u32_e32 v98, v89, v4
	s_nop 6
	v_cvt_pk_bf16_f32 v16, v16, v17
	v_cvt_pk_bf16_f32 v17, v18, v19
	ds_write_b64 v29, v[16:17]
	ds_read_b128 v[16:19], v102
	ds_read_b128 v[30:33], v103 offset:64
	s_waitcnt lgkmcnt(1)
	v_mfma_f32_16x16x32_bf16 v[16:19], v[8:11], v[16:19], 0
	s_waitcnt lgkmcnt(0)
	v_mfma_f32_16x16x32_bf16 v[16:19], v[12:15], v[30:33], v[16:19]
	ds_read_b128 v[30:33], v98
	v_add3_u32 v98, s0, v4, v0
	ds_read_b128 v[98:101], v98 offset:64
	s_waitcnt lgkmcnt(1)
	v_mfma_f32_16x16x32_bf16 v[16:19], v[90:93], v[30:33], v[16:19]
	s_waitcnt lgkmcnt(0)
	v_mfma_f32_16x16x32_bf16 v[16:19], v[94:97], v[98:101], v[16:19]
	s_nop 7
	v_cvt_pk_bf16_f32 v16, v16, v17
	v_cvt_pk_bf16_f32 v17, v18, v19
	ds_write_b64 v29, v[16:17] offset:2304
	ds_read_b128 v[16:19], v34
	ds_read_b128 v[30:33], v35 offset:64
	s_waitcnt lgkmcnt(1)
	v_mfma_f32_16x16x32_bf16 v[16:19], v[8:11], v[16:19], 0
	v_add_u32_e32 v34, v89, v2
	s_waitcnt lgkmcnt(0)
	v_mfma_f32_16x16x32_bf16 v[16:19], v[12:15], v[30:33], v[16:19]
	ds_read_b128 v[30:33], v34
	v_add3_u32 v34, s0, v2, v0
	ds_read_b128 v[98:101], v34 offset:64
	s_waitcnt lgkmcnt(1)
	v_mfma_f32_16x16x32_bf16 v[16:19], v[90:93], v[30:33], v[16:19]
	s_waitcnt lgkmcnt(0)
	v_mfma_f32_16x16x32_bf16 v[16:19], v[94:97], v[98:101], v[16:19]
	s_nop 7
	v_cvt_pk_bf16_f32 v16, v16, v17
	v_cvt_pk_bf16_f32 v17, v18, v19
	ds_write_b64 v29, v[16:17] offset:4608
	ds_read_b128 v[16:19], v104
	ds_read_b128 v[30:33], v105 offset:64
	s_waitcnt lgkmcnt(1)
	v_mfma_f32_16x16x32_bf16 v[8:11], v[8:11], v[16:19], 0
	v_add_u32_e32 v16, v89, v1
	s_waitcnt lgkmcnt(0)
	v_mfma_f32_16x16x32_bf16 v[8:11], v[12:15], v[30:33], v[8:11]
	ds_read_b128 v[12:15], v16
	v_add3_u32 v16, s0, v1, v0
	ds_read_b128 v[16:19], v16 offset:64
	s_waitcnt lgkmcnt(1)
	v_mfma_f32_16x16x32_bf16 v[8:11], v[90:93], v[12:15], v[8:11]
	s_mov_b64 s[0:1], 0
	s_waitcnt lgkmcnt(0)
	v_mfma_f32_16x16x32_bf16 v[8:11], v[94:97], v[16:19], v[8:11]
	s_nop 7
	v_cvt_pk_bf16_f32 v8, v8, v9
	v_cvt_pk_bf16_f32 v9, v10, v11
	ds_write_b64 v29, v[8:9] offset:6912

.Lpa_z0:
	v_mov_b32_e32 v12, 0
	v_mov_b32_e32 v13, 0
	v_mov_b32_e32 v14, 0
	v_mov_b32_e32 v15, 0
	s_branch .LBB0_706

	.amdhsa_kernel _Z6mk_fwd4Args
		.amdhsa_group_segment_fixed_size 0
		.amdhsa_private_segment_fixed_size 0
		.amdhsa_kernarg_size 528
		.amdhsa_user_sgpr_count 2
		.amdhsa_user_sgpr_dispatch_ptr 0
		.amdhsa_user_sgpr_queue_ptr 0
		.amdhsa_user_sgpr_kernarg_segment_ptr 1
		.amdhsa_user_sgpr_dispatch_id 0
		.amdhsa_user_sgpr_kernarg_preload_length 0
		.amdhsa_user_sgpr_kernarg_preload_offset 0
		.amdhsa_user_sgpr_private_segment_size 0
		.amdhsa_uses_dynamic_stack 0
		.amdhsa_enable_private_segment 0
		.amdhsa_system_sgpr_workgroup_id_x 1
		.amdhsa_system_sgpr_workgroup_id_y 0
		.amdhsa_system_sgpr_workgroup_id_z 0
		.amdhsa_system_sgpr_workgroup_info 0
		.amdhsa_system_vgpr_workitem_id 0
		.amdhsa_next_free_vgpr 234
		.amdhsa_next_free_sgpr 102
		.amdhsa_accum_offset 236
		.amdhsa_reserve_vcc 1
		.amdhsa_float_round_mode_32 0
		.amdhsa_float_round_mode_16_64 0
		.amdhsa_float_denorm_mode_32 3
		.amdhsa_float_denorm_mode_16_64 3
		.amdhsa_dx10_clamp 1
		.amdhsa_ieee_mode 1
		.amdhsa_fp16_overflow 0
		.amdhsa_tg_split 0
		.amdhsa_exception_fp_ieee_invalid_op 0
		.amdhsa_exception_fp_denorm_src 0
		.amdhsa_exception_fp_ieee_div_zero 0
		.amdhsa_exception_fp_ieee_overflow 0
		.amdhsa_exception_fp_ieee_underflow 0
		.amdhsa_exception_fp_ieee_inexact 0
		.amdhsa_exception_int_div_zero 0
	.end_amdhsa_kernel

.Lfunc_end0:
	.size	_Z6mk_fwd4Args, .Lfunc_end0-_Z6mk_fwd4Args
	.set _Z6mk_fwd4Args.num_vgpr, 234
	.set _Z6mk_fwd4Args.num_agpr, 0
	.set _Z6mk_fwd4Args.numbered_sgpr, 102
	.set _Z6mk_fwd4Args.num_named_barrier, 0
	.set _Z6mk_fwd4Args.private_seg_size, 0
	.set _Z6mk_fwd4Args.uses_vcc, 1
	.set _Z6mk_fwd4Args.uses_flat_scratch, 0
	.set _Z6mk_fwd4Args.has_dyn_sized_stack, 0
	.set _Z6mk_fwd4Args.has_recursion, 0
	.set _Z6mk_fwd4Args.has_indirect_call, 0

amdhsa.kernels:
  - .agpr_count:     0
    .args:
      - .offset:         0
        .size:           272
        .value_kind:     by_value
      - .offset:         272
        .size:           4
        .value_kind:     hidden_block_count_x
      - .offset:         276
        .size:           4
        .value_kind:     hidden_block_count_y
      - .offset:         280
        .size:           4
        .value_kind:     hidden_block_count_z
      - .offset:         284
        .size:           2
        .value_kind:     hidden_group_size_x
      - .offset:         286
        .size:           2
        .value_kind:     hidden_group_size_y
      - .offset:         288
        .size:           2
        .value_kind:     hidden_group_size_z
      - .offset:         290
        .size:           2
        .value_kind:     hidden_remainder_x
      - .offset:         292
        .size:           2
        .value_kind:     hidden_remainder_y
      - .offset:         294
        .size:           2
        .value_kind:     hidden_remainder_z
      - .offset:         312
        .size:           8
        .value_kind:     hidden_global_offset_x
      - .offset:         320
        .size:           8
        .value_kind:     hidden_global_offset_y
      - .offset:         328
        .size:           8
        .value_kind:     hidden_global_offset_z
      - .offset:         336
        .size:           2
        .value_kind:     hidden_grid_dims
      - .offset:         392
        .size:           4
        .value_kind:     hidden_dynamic_lds_size
    .group_segment_fixed_size: 0
    .kernarg_segment_align: 8
    .kernarg_segment_size: 528
    .language:       OpenCL C
    .language_version:
      - 2
      - 0
    .max_flat_workgroup_size: 512
    .name:           _Z6mk_fwd4Args
    .private_segment_fixed_size: 0
    .sgpr_count:     108
    .sgpr_spill_count: 109
    .symbol:         _Z6mk_fwd4Args.kd
    .uniform_work_group_size: 1
    .uses_dynamic_stack: false
    .vgpr_count:     234
    .vgpr_spill_count: 0
    .wavefront_size: 64
